# M2: the 11 tokens of a unit processed together with the three 64-lane reductions interleaved across tokens (same reduction tree; cross-row step via permlane swaps)
# speedup vs baseline: 1.1151x; 1.0012x over previous
; __device__ __forceinline__ float row16_allsum(float x) {
;     x += dpp_mov<0xB1>(x); x += dpp_mov<0x4E>(x); x += dpp_mov<0x141>(x); x += dpp_mov<0x140>(x); return x;
; }
; __device__ __forceinline__ float wave_sum(float x) {
;     x = row16_allsum(x);
;     const float a = __builtin_bit_cast(float, __builtin_amdgcn_readlane(__builtin_bit_cast(int, x), 0)), b = __builtin_bit_cast(float, __builtin_amdgcn_readlane(__builtin_bit_cast(int, x), 16)),
;                 c = __builtin_bit_cast(float, __builtin_amdgcn_readlane(__builtin_bit_cast(int, x), 32)), d = __builtin_bit_cast(float, __builtin_amdgcn_readlane(__builtin_bit_cast(int, x), 48));
;     return (a + b) + (c + d);
; __device__ __forceinline__ void phase_m2(PP P, int l, LAS unsigned char* lds, const Ids I) {
;     ...
;         for (int i = 0; i < 11; ++i) { const float y = LY[i * 512 + d], rr = LR[i * 512 + d], kf = LK[i * 512 + d], vv = LV[i * 512 + d], g = G[i * 512 + d];
;             const float m = wave_sum(y) * (1.0f / 64.0f), dy = y - m, var = wave_sum(dy * dy) * (1.0f / 64.0f);
;             const float yn = dy * rsqrtf(var + 64e-5f) * lnw + lnb;
.LBB0_494:
	v_add_u32_e32 v253, 0xd200, v198
	v_add_u32_e32 v203, 0x18200, v198
	ds_read2st64_b32 v[212:213], v198 offset0:34 offset1:122
	ds_read2st64_b32 v[214:215], v198 offset0:42 offset1:130
	ds_read2st64_b32 v[216:217], v198 offset0:50 offset1:138
	ds_read2st64_b32 v[218:219], v198 offset0:58 offset1:146
	ds_read2st64_b32 v[220:221], v198 offset0:66 offset1:154
	ds_read2st64_b32 v[222:223], v198 offset0:74 offset1:162
	ds_read2st64_b32 v[224:225], v198 offset0:82 offset1:170
	ds_read2st64_b32 v[226:227], v198 offset0:90 offset1:178
	ds_read2st64_b32 v[228:229], v198 offset0:98 offset1:186
	ds_read2st64_b32 v[230:231], v198 offset0:106 offset1:194
	ds_read2st64_b32 v[232:233], v198 offset0:114 offset1:202
	ds_read_b32 v242, v253
	ds_read_b32 v243, v253 offset:2048
	ds_read_b32 v244, v253 offset:4096
	ds_read_b32 v245, v253 offset:6144
	ds_read_b32 v246, v253 offset:8192
	ds_read_b32 v247, v253 offset:10240
	ds_read_b32 v248, v253 offset:12288
	ds_read_b32 v249, v253 offset:14336
	ds_read_b32 v250, v253 offset:16384
	ds_read_b32 v251, v253 offset:18432
	ds_read_b32 v252, v253 offset:20480
	s_waitcnt lgkmcnt(0)
	v_add_f32_dpp v128, v212, v212 quad_perm:[1,0,3,2] row_mask:0xf bank_mask:0xf bound_ctrl:1
	v_add_f32_dpp v129, v214, v214 quad_perm:[1,0,3,2] row_mask:0xf bank_mask:0xf bound_ctrl:1
	v_add_f32_dpp v130, v216, v216 quad_perm:[1,0,3,2] row_mask:0xf bank_mask:0xf bound_ctrl:1
	v_add_f32_dpp v131, v218, v218 quad_perm:[1,0,3,2] row_mask:0xf bank_mask:0xf bound_ctrl:1
	v_add_f32_dpp v132, v220, v220 quad_perm:[1,0,3,2] row_mask:0xf bank_mask:0xf bound_ctrl:1
	v_add_f32_dpp v133, v222, v222 quad_perm:[1,0,3,2] row_mask:0xf bank_mask:0xf bound_ctrl:1
	v_add_f32_dpp v134, v224, v224 quad_perm:[1,0,3,2] row_mask:0xf bank_mask:0xf bound_ctrl:1
	v_add_f32_dpp v135, v226, v226 quad_perm:[1,0,3,2] row_mask:0xf bank_mask:0xf bound_ctrl:1
	v_add_f32_dpp v136, v228, v228 quad_perm:[1,0,3,2] row_mask:0xf bank_mask:0xf bound_ctrl:1
	v_add_f32_dpp v137, v230, v230 quad_perm:[1,0,3,2] row_mask:0xf bank_mask:0xf bound_ctrl:1
	v_add_f32_dpp v138, v232, v232 quad_perm:[1,0,3,2] row_mask:0xf bank_mask:0xf bound_ctrl:1
	v_add_f32_dpp v128, v128, v128 quad_perm:[2,3,0,1] row_mask:0xf bank_mask:0xf bound_ctrl:1
	v_add_f32_dpp v129, v129, v129 quad_perm:[2,3,0,1] row_mask:0xf bank_mask:0xf bound_ctrl:1
	v_add_f32_dpp v130, v130, v130 quad_perm:[2,3,0,1] row_mask:0xf bank_mask:0xf bound_ctrl:1
	v_add_f32_dpp v131, v131, v131 quad_perm:[2,3,0,1] row_mask:0xf bank_mask:0xf bound_ctrl:1
	v_add_f32_dpp v132, v132, v132 quad_perm:[2,3,0,1] row_mask:0xf bank_mask:0xf bound_ctrl:1
	v_add_f32_dpp v133, v133, v133 quad_perm:[2,3,0,1] row_mask:0xf bank_mask:0xf bound_ctrl:1
	v_add_f32_dpp v134, v134, v134 quad_perm:[2,3,0,1] row_mask:0xf bank_mask:0xf bound_ctrl:1
	v_add_f32_dpp v135, v135, v135 quad_perm:[2,3,0,1] row_mask:0xf bank_mask:0xf bound_ctrl:1
	v_add_f32_dpp v136, v136, v136 quad_perm:[2,3,0,1] row_mask:0xf bank_mask:0xf bound_ctrl:1
	v_add_f32_dpp v137, v137, v137 quad_perm:[2,3,0,1] row_mask:0xf bank_mask:0xf bound_ctrl:1
	v_add_f32_dpp v138, v138, v138 quad_perm:[2,3,0,1] row_mask:0xf bank_mask:0xf bound_ctrl:1
	v_add_f32_dpp v128, v128, v128 row_half_mirror row_mask:0xf bank_mask:0xf bound_ctrl:1
	v_add_f32_dpp v129, v129, v129 row_half_mirror row_mask:0xf bank_mask:0xf bound_ctrl:1
	v_add_f32_dpp v130, v130, v130 row_half_mirror row_mask:0xf bank_mask:0xf bound_ctrl:1
	v_add_f32_dpp v131, v131, v131 row_half_mirror row_mask:0xf bank_mask:0xf bound_ctrl:1
	v_add_f32_dpp v132, v132, v132 row_half_mirror row_mask:0xf bank_mask:0xf bound_ctrl:1
	v_add_f32_dpp v133, v133, v133 row_half_mirror row_mask:0xf bank_mask:0xf bound_ctrl:1
	v_add_f32_dpp v134, v134, v134 row_half_mirror row_mask:0xf bank_mask:0xf bound_ctrl:1
	v_add_f32_dpp v135, v135, v135 row_half_mirror row_mask:0xf bank_mask:0xf bound_ctrl:1
	v_add_f32_dpp v136, v136, v136 row_half_mirror row_mask:0xf bank_mask:0xf bound_ctrl:1
	v_add_f32_dpp v137, v137, v137 row_half_mirror row_mask:0xf bank_mask:0xf bound_ctrl:1
	v_add_f32_dpp v138, v138, v138 row_half_mirror row_mask:0xf bank_mask:0xf bound_ctrl:1
	v_add_f32_dpp v128, v128, v128 row_mirror row_mask:0xf bank_mask:0xf bound_ctrl:1
	v_add_f32_dpp v129, v129, v129 row_mirror row_mask:0xf bank_mask:0xf bound_ctrl:1
	v_add_f32_dpp v130, v130, v130 row_mirror row_mask:0xf bank_mask:0xf bound_ctrl:1
	v_add_f32_dpp v131, v131, v131 row_mirror row_mask:0xf bank_mask:0xf bound_ctrl:1
	v_add_f32_dpp v132, v132, v132 row_mirror row_mask:0xf bank_mask:0xf bound_ctrl:1
	v_add_f32_dpp v133, v133, v133 row_mirror row_mask:0xf bank_mask:0xf bound_ctrl:1
	v_add_f32_dpp v134, v134, v134 row_mirror row_mask:0xf bank_mask:0xf bound_ctrl:1
	v_add_f32_dpp v135, v135, v135 row_mirror row_mask:0xf bank_mask:0xf bound_ctrl:1
	v_add_f32_dpp v136, v136, v136 row_mirror row_mask:0xf bank_mask:0xf bound_ctrl:1
	v_add_f32_dpp v137, v137, v137 row_mirror row_mask:0xf bank_mask:0xf bound_ctrl:1
	v_add_f32_dpp v138, v138, v138 row_mirror row_mask:0xf bank_mask:0xf bound_ctrl:1
	v_mul_f32_e32 v213, v213, v242
	v_mul_f32_e32 v215, v215, v243
	v_mul_f32_e32 v217, v217, v244
	v_mul_f32_e32 v219, v219, v245
	v_mul_f32_e32 v221, v221, v246
	v_mul_f32_e32 v223, v223, v247
	v_mul_f32_e32 v225, v225, v248
	v_mul_f32_e32 v227, v227, v249
	v_mul_f32_e32 v229, v229, v250
	v_mul_f32_e32 v231, v231, v251
	v_mul_f32_e32 v233, v233, v252
	v_mov_b32_e32 v176, v128
	v_mov_b32_e32 v177, v129
	v_mov_b32_e32 v178, v130
	v_mov_b32_e32 v179, v131
	v_mov_b32_e32 v180, v132
	v_mov_b32_e32 v181, v133
	v_mov_b32_e32 v182, v134
	v_mov_b32_e32 v183, v135
	v_mov_b32_e32 v204, v136
	v_mov_b32_e32 v205, v137
; __device__ __forceinline__ float row16_allsum(float x) {
;     x += dpp_mov<0xB1>(x); x += dpp_mov<0x4E>(x); x += dpp_mov<0x141>(x); x += dpp_mov<0x140>(x); return x;
; }
; __device__ __forceinline__ float wave_sum(float x) {
;     x = row16_allsum(x);
;     const float a = __builtin_bit_cast(float, __builtin_amdgcn_readlane(__builtin_bit_cast(int, x), 0)), b = __builtin_bit_cast(float, __builtin_amdgcn_readlane(__builtin_bit_cast(int, x), 16)),
;                 c = __builtin_bit_cast(float, __builtin_amdgcn_readlane(__builtin_bit_cast(int, x), 32)), d = __builtin_bit_cast(float, __builtin_amdgcn_readlane(__builtin_bit_cast(int, x), 48));
;     return (a + b) + (c + d);
; __device__ __forceinline__ void phase_m2(PP P, int l, LAS unsigned char* lds, const Ids I) {
;     ...
;             const float m = wave_sum(y) * (1.0f / 64.0f), dy = y - m, var = wave_sum(dy * dy) * (1.0f / 64.0f);
;             const float yn = dy * rsqrtf(var + 64e-5f) * lnw + lnb;
	v_mov_b32_e32 v206, v138
	v_permlane16_swap_b32 v128, v176
	v_permlane16_swap_b32 v129, v177
	v_permlane16_swap_b32 v130, v178
	v_permlane16_swap_b32 v131, v179
	v_permlane16_swap_b32 v132, v180
	v_permlane16_swap_b32 v133, v181
	v_permlane16_swap_b32 v134, v182
	v_permlane16_swap_b32 v135, v183
	v_permlane16_swap_b32 v136, v204
	v_permlane16_swap_b32 v137, v205
	v_permlane16_swap_b32 v138, v206
	v_add_f32_e32 v128, v128, v176
	v_add_f32_e32 v129, v129, v177
	v_add_f32_e32 v130, v130, v178
	v_add_f32_e32 v131, v131, v179
	v_add_f32_e32 v132, v132, v180
	v_add_f32_e32 v133, v133, v181
	v_add_f32_e32 v134, v134, v182
	v_add_f32_e32 v135, v135, v183
	v_add_f32_e32 v136, v136, v204
	v_add_f32_e32 v137, v137, v205
	v_add_f32_e32 v138, v138, v206
	v_mov_b32_e32 v176, v128
	v_mov_b32_e32 v177, v129
	v_mov_b32_e32 v178, v130
	v_mov_b32_e32 v179, v131
	v_mov_b32_e32 v180, v132
	v_mov_b32_e32 v181, v133
	v_mov_b32_e32 v182, v134
	v_mov_b32_e32 v183, v135
	v_mov_b32_e32 v204, v136
	v_mov_b32_e32 v205, v137
	v_mov_b32_e32 v206, v138
	v_permlane32_swap_b32 v128, v176
	v_permlane32_swap_b32 v129, v177
	v_permlane32_swap_b32 v130, v178
	v_permlane32_swap_b32 v131, v179
	v_permlane32_swap_b32 v132, v180
	v_permlane32_swap_b32 v133, v181
	v_permlane32_swap_b32 v134, v182
	v_permlane32_swap_b32 v135, v183
	v_permlane32_swap_b32 v136, v204
	v_permlane32_swap_b32 v137, v205
	v_permlane32_swap_b32 v138, v206
	v_add_f32_e32 v128, v128, v176
	v_add_f32_e32 v129, v129, v177
	v_add_f32_e32 v130, v130, v178
	v_add_f32_e32 v131, v131, v179
	v_add_f32_e32 v132, v132, v180
	v_add_f32_e32 v133, v133, v181
	v_add_f32_e32 v134, v134, v182
	v_add_f32_e32 v135, v135, v183
	v_add_f32_e32 v136, v136, v204
	v_add_f32_e32 v137, v137, v205
	v_add_f32_e32 v138, v138, v206
	v_fmamk_f32 v212, v128, 0xbc800000, v212
	v_fmamk_f32 v214, v129, 0xbc800000, v214
	v_fmamk_f32 v216, v130, 0xbc800000, v216
	v_fmamk_f32 v218, v131, 0xbc800000, v218
	v_fmamk_f32 v220, v132, 0xbc800000, v220
	v_fmamk_f32 v222, v133, 0xbc800000, v222
	v_fmamk_f32 v224, v134, 0xbc800000, v224
	v_fmamk_f32 v226, v135, 0xbc800000, v226
	v_fmamk_f32 v228, v136, 0xbc800000, v228
	v_fmamk_f32 v230, v137, 0xbc800000, v230
	v_fmamk_f32 v232, v138, 0xbc800000, v232
	v_mul_f32_e32 v128, v212, v212
	v_mul_f32_e32 v129, v214, v214
	v_mul_f32_e32 v130, v216, v216
	v_mul_f32_e32 v131, v218, v218
	v_mul_f32_e32 v132, v220, v220
	v_mul_f32_e32 v133, v222, v222
	v_mul_f32_e32 v134, v224, v224
	v_mul_f32_e32 v135, v226, v226
	v_mul_f32_e32 v136, v228, v228
	v_mul_f32_e32 v137, v230, v230
	v_mul_f32_e32 v138, v232, v232
	v_mov_b32_dpp v128, v128 quad_perm:[1,0,3,2] row_mask:0xf bank_mask:0xf bound_ctrl:1
	v_mov_b32_dpp v129, v129 quad_perm:[1,0,3,2] row_mask:0xf bank_mask:0xf bound_ctrl:1
	v_mov_b32_dpp v130, v130 quad_perm:[1,0,3,2] row_mask:0xf bank_mask:0xf bound_ctrl:1
	v_mov_b32_dpp v131, v131 quad_perm:[1,0,3,2] row_mask:0xf bank_mask:0xf bound_ctrl:1
	v_mov_b32_dpp v132, v132 quad_perm:[1,0,3,2] row_mask:0xf bank_mask:0xf bound_ctrl:1
	v_mov_b32_dpp v133, v133 quad_perm:[1,0,3,2] row_mask:0xf bank_mask:0xf bound_ctrl:1
	v_mov_b32_dpp v134, v134 quad_perm:[1,0,3,2] row_mask:0xf bank_mask:0xf bound_ctrl:1
	v_mov_b32_dpp v135, v135 quad_perm:[1,0,3,2] row_mask:0xf bank_mask:0xf bound_ctrl:1
	v_mov_b32_dpp v136, v136 quad_perm:[1,0,3,2] row_mask:0xf bank_mask:0xf bound_ctrl:1
	v_mov_b32_dpp v137, v137 quad_perm:[1,0,3,2] row_mask:0xf bank_mask:0xf bound_ctrl:1
	v_mov_b32_dpp v138, v138 quad_perm:[1,0,3,2] row_mask:0xf bank_mask:0xf bound_ctrl:1
	v_fmac_f32_e32 v128, v212, v212
	v_fmac_f32_e32 v129, v214, v214
	v_fmac_f32_e32 v130, v216, v216
	v_fmac_f32_e32 v131, v218, v218
	v_fmac_f32_e32 v132, v220, v220
	v_fmac_f32_e32 v133, v222, v222
	v_fmac_f32_e32 v134, v224, v224
	v_fmac_f32_e32 v135, v226, v226
	v_fmac_f32_e32 v136, v228, v228
	v_fmac_f32_e32 v137, v230, v230
	v_fmac_f32_e32 v138, v232, v232
	v_add_f32_dpp v128, v128, v128 quad_perm:[2,3,0,1] row_mask:0xf bank_mask:0xf bound_ctrl:1
	v_add_f32_dpp v129, v129, v129 quad_perm:[2,3,0,1] row_mask:0xf bank_mask:0xf bound_ctrl:1
	v_add_f32_dpp v130, v130, v130 quad_perm:[2,3,0,1] row_mask:0xf bank_mask:0xf bound_ctrl:1
	v_add_f32_dpp v131, v131, v131 quad_perm:[2,3,0,1] row_mask:0xf bank_mask:0xf bound_ctrl:1
	v_add_f32_dpp v132, v132, v132 quad_perm:[2,3,0,1] row_mask:0xf bank_mask:0xf bound_ctrl:1
	v_add_f32_dpp v133, v133, v133 quad_perm:[2,3,0,1] row_mask:0xf bank_mask:0xf bound_ctrl:1
	v_add_f32_dpp v134, v134, v134 quad_perm:[2,3,0,1] row_mask:0xf bank_mask:0xf bound_ctrl:1
	v_add_f32_dpp v135, v135, v135 quad_perm:[2,3,0,1] row_mask:0xf bank_mask:0xf bound_ctrl:1
	v_add_f32_dpp v136, v136, v136 quad_perm:[2,3,0,1] row_mask:0xf bank_mask:0xf bound_ctrl:1
	v_add_f32_dpp v137, v137, v137 quad_perm:[2,3,0,1] row_mask:0xf bank_mask:0xf bound_ctrl:1
	v_add_f32_dpp v138, v138, v138 quad_perm:[2,3,0,1] row_mask:0xf bank_mask:0xf bound_ctrl:1
	v_add_f32_dpp v128, v128, v128 row_half_mirror row_mask:0xf bank_mask:0xf bound_ctrl:1
	v_add_f32_dpp v129, v129, v129 row_half_mirror row_mask:0xf bank_mask:0xf bound_ctrl:1
	v_add_f32_dpp v130, v130, v130 row_half_mirror row_mask:0xf bank_mask:0xf bound_ctrl:1
	v_add_f32_dpp v131, v131, v131 row_half_mirror row_mask:0xf bank_mask:0xf bound_ctrl:1
	v_add_f32_dpp v132, v132, v132 row_half_mirror row_mask:0xf bank_mask:0xf bound_ctrl:1
	v_add_f32_dpp v133, v133, v133 row_half_mirror row_mask:0xf bank_mask:0xf bound_ctrl:1
	v_add_f32_dpp v134, v134, v134 row_half_mirror row_mask:0xf bank_mask:0xf bound_ctrl:1
	v_add_f32_dpp v135, v135, v135 row_half_mirror row_mask:0xf bank_mask:0xf bound_ctrl:1
; __device__ __forceinline__ float row16_allsum(float x) {
;     x += dpp_mov<0xB1>(x); x += dpp_mov<0x4E>(x); x += dpp_mov<0x141>(x); x += dpp_mov<0x140>(x); return x;
; }
; __device__ __forceinline__ float wave_sum(float x) {
;     x = row16_allsum(x);
;     const float a = __builtin_bit_cast(float, __builtin_amdgcn_readlane(__builtin_bit_cast(int, x), 0)), b = __builtin_bit_cast(float, __builtin_amdgcn_readlane(__builtin_bit_cast(int, x), 16)),
;                 c = __builtin_bit_cast(float, __builtin_amdgcn_readlane(__builtin_bit_cast(int, x), 32)), d = __builtin_bit_cast(float, __builtin_amdgcn_readlane(__builtin_bit_cast(int, x), 48));
;     return (a + b) + (c + d);
; __device__ __forceinline__ void phase_m2(PP P, int l, LAS unsigned char* lds, const Ids I) {
;     ...
;             const float m = wave_sum(y) * (1.0f / 64.0f), dy = y - m, var = wave_sum(dy * dy) * (1.0f / 64.0f);
;             const float yn = dy * rsqrtf(var + 64e-5f) * lnw + lnb;
;             const float bs = wave_sum(rr * kf * rk);
	v_add_f32_dpp v136, v136, v136 row_half_mirror row_mask:0xf bank_mask:0xf bound_ctrl:1
	v_add_f32_dpp v137, v137, v137 row_half_mirror row_mask:0xf bank_mask:0xf bound_ctrl:1
	v_add_f32_dpp v138, v138, v138 row_half_mirror row_mask:0xf bank_mask:0xf bound_ctrl:1
	v_add_f32_dpp v128, v128, v128 row_mirror row_mask:0xf bank_mask:0xf bound_ctrl:1
	v_add_f32_dpp v129, v129, v129 row_mirror row_mask:0xf bank_mask:0xf bound_ctrl:1
	v_add_f32_dpp v130, v130, v130 row_mirror row_mask:0xf bank_mask:0xf bound_ctrl:1
	v_add_f32_dpp v131, v131, v131 row_mirror row_mask:0xf bank_mask:0xf bound_ctrl:1
	v_add_f32_dpp v132, v132, v132 row_mirror row_mask:0xf bank_mask:0xf bound_ctrl:1
	v_add_f32_dpp v133, v133, v133 row_mirror row_mask:0xf bank_mask:0xf bound_ctrl:1
	v_add_f32_dpp v134, v134, v134 row_mirror row_mask:0xf bank_mask:0xf bound_ctrl:1
	v_add_f32_dpp v135, v135, v135 row_mirror row_mask:0xf bank_mask:0xf bound_ctrl:1
	v_add_f32_dpp v136, v136, v136 row_mirror row_mask:0xf bank_mask:0xf bound_ctrl:1
	v_add_f32_dpp v137, v137, v137 row_mirror row_mask:0xf bank_mask:0xf bound_ctrl:1
	v_add_f32_dpp v138, v138, v138 row_mirror row_mask:0xf bank_mask:0xf bound_ctrl:1
	v_mul_f32_e32 v242, v155, v213
	v_mul_f32_e32 v243, v155, v215
	v_mul_f32_e32 v244, v155, v217
	v_mul_f32_e32 v245, v155, v219
	v_mul_f32_e32 v246, v155, v221
	v_mul_f32_e32 v247, v155, v223
	v_mul_f32_e32 v248, v155, v225
	v_mul_f32_e32 v249, v155, v227
	v_mul_f32_e32 v250, v155, v229
	v_mul_f32_e32 v251, v155, v231
	v_mul_f32_e32 v252, v155, v233
	v_mov_b32_e32 v176, v128
	v_mov_b32_e32 v177, v129
	v_mov_b32_e32 v178, v130
	v_mov_b32_e32 v179, v131
	v_mov_b32_e32 v180, v132
	v_mov_b32_e32 v181, v133
	v_mov_b32_e32 v182, v134
	v_mov_b32_e32 v183, v135
	v_mov_b32_e32 v204, v136
	v_mov_b32_e32 v205, v137
	v_mov_b32_e32 v206, v138
	v_permlane16_swap_b32 v128, v176
	v_permlane16_swap_b32 v129, v177
	v_permlane16_swap_b32 v130, v178
	v_permlane16_swap_b32 v131, v179
	v_permlane16_swap_b32 v132, v180
	v_permlane16_swap_b32 v133, v181
	v_permlane16_swap_b32 v134, v182
	v_permlane16_swap_b32 v135, v183
	v_permlane16_swap_b32 v136, v204
	v_permlane16_swap_b32 v137, v205
	v_permlane16_swap_b32 v138, v206
	v_add_f32_e32 v128, v128, v176
	v_add_f32_e32 v129, v129, v177
	v_add_f32_e32 v130, v130, v178
	v_add_f32_e32 v131, v131, v179
	v_add_f32_e32 v132, v132, v180
	v_add_f32_e32 v133, v133, v181
	v_add_f32_e32 v134, v134, v182
	v_add_f32_e32 v135, v135, v183
	v_add_f32_e32 v136, v136, v204
	v_add_f32_e32 v137, v137, v205
	v_add_f32_e32 v138, v138, v206
	v_mov_b32_e32 v176, v128
	v_mov_b32_e32 v177, v129
	v_mov_b32_e32 v178, v130
	v_mov_b32_e32 v179, v131
	v_mov_b32_e32 v180, v132
	v_mov_b32_e32 v181, v133
	v_mov_b32_e32 v182, v134
	v_mov_b32_e32 v183, v135
	v_mov_b32_e32 v204, v136
	v_mov_b32_e32 v205, v137
	v_mov_b32_e32 v206, v138
	v_permlane32_swap_b32 v128, v176
	v_permlane32_swap_b32 v129, v177
	v_permlane32_swap_b32 v130, v178
	v_permlane32_swap_b32 v131, v179
	v_permlane32_swap_b32 v132, v180
	v_permlane32_swap_b32 v133, v181
	v_permlane32_swap_b32 v134, v182
	v_permlane32_swap_b32 v135, v183
	v_permlane32_swap_b32 v136, v204
	v_permlane32_swap_b32 v137, v205
	v_permlane32_swap_b32 v138, v206
	v_add_f32_e32 v128, v128, v176
	v_add_f32_e32 v129, v129, v177
	v_add_f32_e32 v130, v130, v178
	v_add_f32_e32 v131, v131, v179
	v_add_f32_e32 v132, v132, v180
	v_add_f32_e32 v133, v133, v181
	v_add_f32_e32 v134, v134, v182
	v_add_f32_e32 v135, v135, v183
	v_add_f32_e32 v136, v136, v204
	v_add_f32_e32 v137, v137, v205
	v_add_f32_e32 v138, v138, v206
	v_mov_b32_e32 v176, 0x3a27c5ac
	v_fmamk_f32 v128, v128, 0x3c800000, v176
	v_fmamk_f32 v129, v129, 0x3c800000, v176
	v_fmamk_f32 v130, v130, 0x3c800000, v176
	v_fmamk_f32 v131, v131, 0x3c800000, v176
	v_fmamk_f32 v132, v132, 0x3c800000, v176
	v_fmamk_f32 v133, v133, 0x3c800000, v176
	v_fmamk_f32 v134, v134, 0x3c800000, v176
	v_fmamk_f32 v135, v135, 0x3c800000, v176
	v_fmamk_f32 v136, v136, 0x3c800000, v176
	v_fmamk_f32 v137, v137, 0x3c800000, v176
	v_fmamk_f32 v138, v138, 0x3c800000, v176
	v_cmp_gt_f32_e32 vcc, s58, v128
	v_cmp_gt_f32_e64 s[22:23], s58, v129
	v_cmp_gt_f32_e64 s[24:25], s58, v130
	v_cmp_gt_f32_e64 s[26:27], s58, v131
	v_cmp_gt_f32_e64 s[28:29], s58, v132
	v_cmp_gt_f32_e64 s[0:1], s58, v133
	v_mul_f32_e32 v177, 0x4b800000, v128
	v_mul_f32_e32 v178, 0x4b800000, v129
	v_mul_f32_e32 v179, 0x4b800000, v130
	v_mul_f32_e32 v180, 0x4b800000, v131
	v_mul_f32_e32 v181, 0x4b800000, v132
	v_mul_f32_e32 v182, 0x4b800000, v133
	v_cndmask_b32_e32 v128, v128, v177, vcc
	v_cndmask_b32_e64 v129, v129, v178, s[22:23]
	v_cndmask_b32_e64 v130, v130, v179, s[24:25]
	v_cndmask_b32_e64 v131, v131, v180, s[26:27]
	v_cndmask_b32_e64 v132, v132, v181, s[28:29]
	v_cndmask_b32_e64 v133, v133, v182, s[0:1]
	v_rsq_f32_e32 v128, v128
	v_rsq_f32_e32 v129, v129
	v_rsq_f32_e32 v130, v130
	v_rsq_f32_e32 v131, v131
	v_rsq_f32_e32 v132, v132
	v_rsq_f32_e32 v133, v133
	v_mul_f32_e32 v177, 0x45800000, v128
	v_mul_f32_e32 v178, 0x45800000, v129
	v_mul_f32_e32 v179, 0x45800000, v130
	v_mul_f32_e32 v180, 0x45800000, v131
	v_mul_f32_e32 v181, 0x45800000, v132
	v_mul_f32_e32 v182, 0x45800000, v133
	v_cndmask_b32_e32 v128, v128, v177, vcc
	v_cndmask_b32_e64 v129, v129, v178, s[22:23]
	v_cndmask_b32_e64 v130, v130, v179, s[24:25]
	v_cndmask_b32_e64 v131, v131, v180, s[26:27]
	v_cndmask_b32_e64 v132, v132, v181, s[28:29]
	v_cndmask_b32_e64 v133, v133, v182, s[0:1]
	v_cmp_gt_f32_e32 vcc, s58, v134
	v_cmp_gt_f32_e64 s[22:23], s58, v135
	v_cmp_gt_f32_e64 s[24:25], s58, v136
	v_cmp_gt_f32_e64 s[26:27], s58, v137
	v_cmp_gt_f32_e64 s[28:29], s58, v138
	v_mul_f32_e32 v177, 0x4b800000, v134
; __device__ __forceinline__ float row16_allsum(float x) {
;     x += dpp_mov<0xB1>(x); x += dpp_mov<0x4E>(x); x += dpp_mov<0x141>(x); x += dpp_mov<0x140>(x); return x;
; }
; __device__ __forceinline__ float wave_sum(float x) {
;     x = row16_allsum(x);
;     const float a = __builtin_bit_cast(float, __builtin_amdgcn_readlane(__builtin_bit_cast(int, x), 0)), b = __builtin_bit_cast(float, __builtin_amdgcn_readlane(__builtin_bit_cast(int, x), 16)),
;                 c = __builtin_bit_cast(float, __builtin_amdgcn_readlane(__builtin_bit_cast(int, x), 32)), d = __builtin_bit_cast(float, __builtin_amdgcn_readlane(__builtin_bit_cast(int, x), 48));
;     return (a + b) + (c + d);
; __device__ __forceinline__ void phase_m2(PP P, int l, LAS unsigned char* lds, const Ids I) {
;     ...
;             const float yn = dy * rsqrtf(var + 64e-5f) * lnw + lnb;
;             const float bs = wave_sum(rr * kf * rk);
	v_mul_f32_e32 v178, 0x4b800000, v135
	v_mul_f32_e32 v179, 0x4b800000, v136
	v_mul_f32_e32 v180, 0x4b800000, v137
	v_mul_f32_e32 v181, 0x4b800000, v138
	v_cndmask_b32_e32 v134, v134, v177, vcc
	v_cndmask_b32_e64 v135, v135, v178, s[22:23]
	v_cndmask_b32_e64 v136, v136, v179, s[24:25]
	v_cndmask_b32_e64 v137, v137, v180, s[26:27]
	v_cndmask_b32_e64 v138, v138, v181, s[28:29]
	v_rsq_f32_e32 v134, v134
	v_rsq_f32_e32 v135, v135
	v_rsq_f32_e32 v136, v136
	v_rsq_f32_e32 v137, v137
	v_rsq_f32_e32 v138, v138
	v_mul_f32_e32 v177, 0x45800000, v134
	v_mul_f32_e32 v178, 0x45800000, v135
	v_mul_f32_e32 v179, 0x45800000, v136
	v_mul_f32_e32 v180, 0x45800000, v137
	v_mul_f32_e32 v181, 0x45800000, v138
	v_cndmask_b32_e32 v134, v134, v177, vcc
	v_cndmask_b32_e64 v135, v135, v178, s[22:23]
	v_cndmask_b32_e64 v136, v136, v179, s[24:25]
	v_cndmask_b32_e64 v137, v137, v180, s[26:27]
	v_cndmask_b32_e64 v138, v138, v181, s[28:29]
	v_mul_f32_e32 v212, v212, v128
	v_mul_f32_e32 v214, v214, v129
	v_mul_f32_e32 v216, v216, v130
	v_mul_f32_e32 v218, v218, v131
	v_mul_f32_e32 v220, v220, v132
	v_mul_f32_e32 v222, v222, v133
	v_mul_f32_e32 v224, v224, v134
	v_mul_f32_e32 v226, v226, v135
	v_mul_f32_e32 v228, v228, v136
	v_mul_f32_e32 v230, v230, v137
	v_mul_f32_e32 v232, v232, v138
	v_mov_b32_dpp v242, v242 quad_perm:[1,0,3,2] row_mask:0xf bank_mask:0xf bound_ctrl:1
	v_mov_b32_dpp v243, v243 quad_perm:[1,0,3,2] row_mask:0xf bank_mask:0xf bound_ctrl:1
	v_mov_b32_dpp v244, v244 quad_perm:[1,0,3,2] row_mask:0xf bank_mask:0xf bound_ctrl:1
	v_mov_b32_dpp v245, v245 quad_perm:[1,0,3,2] row_mask:0xf bank_mask:0xf bound_ctrl:1
	v_mov_b32_dpp v246, v246 quad_perm:[1,0,3,2] row_mask:0xf bank_mask:0xf bound_ctrl:1
	v_mov_b32_dpp v247, v247 quad_perm:[1,0,3,2] row_mask:0xf bank_mask:0xf bound_ctrl:1
	v_mov_b32_dpp v248, v248 quad_perm:[1,0,3,2] row_mask:0xf bank_mask:0xf bound_ctrl:1
	v_mov_b32_dpp v249, v249 quad_perm:[1,0,3,2] row_mask:0xf bank_mask:0xf bound_ctrl:1
	v_mov_b32_dpp v250, v250 quad_perm:[1,0,3,2] row_mask:0xf bank_mask:0xf bound_ctrl:1
	v_mov_b32_dpp v251, v251 quad_perm:[1,0,3,2] row_mask:0xf bank_mask:0xf bound_ctrl:1
	v_mov_b32_dpp v252, v252 quad_perm:[1,0,3,2] row_mask:0xf bank_mask:0xf bound_ctrl:1
	v_fmac_f32_e32 v242, v155, v213
	v_fmac_f32_e32 v243, v155, v215
	v_fmac_f32_e32 v244, v155, v217
	v_fmac_f32_e32 v245, v155, v219
	v_fmac_f32_e32 v246, v155, v221
	v_fmac_f32_e32 v247, v155, v223
	v_fmac_f32_e32 v248, v155, v225
	v_fmac_f32_e32 v249, v155, v227
	v_fmac_f32_e32 v250, v155, v229
	v_fmac_f32_e32 v251, v155, v231
	v_fmac_f32_e32 v252, v155, v233
	ds_read_b32 v213, v253 offset:22528
	ds_read_b32 v215, v253 offset:24576
	ds_read_b32 v217, v253 offset:26624
	ds_read_b32 v219, v253 offset:28672
	ds_read_b32 v221, v253 offset:30720
	ds_read_b32 v223, v253 offset:32768
	ds_read_b32 v225, v253 offset:34816
	ds_read_b32 v227, v253 offset:36864
	ds_read_b32 v229, v253 offset:38912
	ds_read_b32 v231, v253 offset:40960
	ds_read_b32 v233, v253 offset:43008
	ds_read_b32 v128, v203
	ds_read_b32 v129, v203 offset:2048
	ds_read_b32 v130, v203 offset:4096
	ds_read_b32 v131, v203 offset:6144
	ds_read_b32 v132, v203 offset:8192
	ds_read_b32 v133, v203 offset:10240
	ds_read_b32 v134, v203 offset:12288
	ds_read_b32 v135, v203 offset:14336
	ds_read_b32 v136, v203 offset:16384
	ds_read_b32 v137, v203 offset:18432
	ds_read_b32 v138, v203 offset:20480
	v_add_f32_dpp v242, v242, v242 quad_perm:[2,3,0,1] row_mask:0xf bank_mask:0xf bound_ctrl:1
	v_add_f32_dpp v243, v243, v243 quad_perm:[2,3,0,1] row_mask:0xf bank_mask:0xf bound_ctrl:1
	v_add_f32_dpp v244, v244, v244 quad_perm:[2,3,0,1] row_mask:0xf bank_mask:0xf bound_ctrl:1
	v_add_f32_dpp v245, v245, v245 quad_perm:[2,3,0,1] row_mask:0xf bank_mask:0xf bound_ctrl:1
	v_add_f32_dpp v246, v246, v246 quad_perm:[2,3,0,1] row_mask:0xf bank_mask:0xf bound_ctrl:1
	v_add_f32_dpp v247, v247, v247 quad_perm:[2,3,0,1] row_mask:0xf bank_mask:0xf bound_ctrl:1
	v_add_f32_dpp v248, v248, v248 quad_perm:[2,3,0,1] row_mask:0xf bank_mask:0xf bound_ctrl:1
	v_add_f32_dpp v249, v249, v249 quad_perm:[2,3,0,1] row_mask:0xf bank_mask:0xf bound_ctrl:1
	v_add_f32_dpp v250, v250, v250 quad_perm:[2,3,0,1] row_mask:0xf bank_mask:0xf bound_ctrl:1
	v_add_f32_dpp v251, v251, v251 quad_perm:[2,3,0,1] row_mask:0xf bank_mask:0xf bound_ctrl:1
	v_add_f32_dpp v252, v252, v252 quad_perm:[2,3,0,1] row_mask:0xf bank_mask:0xf bound_ctrl:1
	v_add_f32_dpp v242, v242, v242 row_half_mirror row_mask:0xf bank_mask:0xf bound_ctrl:1
	v_add_f32_dpp v243, v243, v243 row_half_mirror row_mask:0xf bank_mask:0xf bound_ctrl:1
	v_add_f32_dpp v244, v244, v244 row_half_mirror row_mask:0xf bank_mask:0xf bound_ctrl:1
	v_add_f32_dpp v245, v245, v245 row_half_mirror row_mask:0xf bank_mask:0xf bound_ctrl:1
	v_add_f32_dpp v246, v246, v246 row_half_mirror row_mask:0xf bank_mask:0xf bound_ctrl:1
	v_add_f32_dpp v247, v247, v247 row_half_mirror row_mask:0xf bank_mask:0xf bound_ctrl:1
	v_add_f32_dpp v248, v248, v248 row_half_mirror row_mask:0xf bank_mask:0xf bound_ctrl:1
	v_add_f32_dpp v249, v249, v249 row_half_mirror row_mask:0xf bank_mask:0xf bound_ctrl:1
	v_add_f32_dpp v250, v250, v250 row_half_mirror row_mask:0xf bank_mask:0xf bound_ctrl:1
	v_add_f32_dpp v251, v251, v251 row_half_mirror row_mask:0xf bank_mask:0xf bound_ctrl:1
	v_add_f32_dpp v252, v252, v252 row_half_mirror row_mask:0xf bank_mask:0xf bound_ctrl:1
	v_add_f32_dpp v242, v242, v242 row_mirror row_mask:0xf bank_mask:0xf bound_ctrl:1
	v_add_f32_dpp v243, v243, v243 row_mirror row_mask:0xf bank_mask:0xf bound_ctrl:1
; #define LAS __attribute__((address_space(3)))
; __device__ __forceinline__ unsigned cvt_pk_bf16(float lo, float hi) { unsigned r; asm("v_cvt_pk_bf16_f32 %0, %1, %2" : "=v"(r) : "v"(lo), "v"(hi)); return r; }
; __device__ __forceinline__ void phase_m2(PP P, int l, LAS unsigned char* lds, const Ids I) {
;     ...
;         for (int i = 0; i < 11; ++i) { const float y = LY[i * 512 + d], rr = LR[i * 512 + d], kf = LK[i * 512 + d], vv = LV[i * 512 + d], g = G[i * 512 + d];
;             const float m = wave_sum(y) * (1.0f / 64.0f), dy = y - m, var = wave_sum(dy * dy) * (1.0f / 64.0f);
;             const float yn = dy * rsqrtf(var + 64e-5f) * lnw + lnb;
;             const float bs = wave_sum(rr * kf * rk);
;             LY[i * 512 + d] = (yn + bs * vv) * g; }
;         __syncthreads();
; #pragma unroll
;         for (int i = 0; i < 2; ++i) { const int idx = tid + 512 * i; if (idx < 11 * 64) { const int tok = idx >> 6, c8 = (idx & 63) * 8; const LAS float* lp = LY + tok * 512 + c8; const f32x4 a = *(const LAS f32x4*)lp, b = *(const LAS f32x4*)(lp + 4);
;           u32x4 w; w.x = cvt_pk_bf16(a[0], a[1]); w.y = cvt_pk_bf16(a[2], a[3]); w.z = cvt_pk_bf16(b[0], b[1]); w.w = cvt_pk_bf16(b[2], b[3]);
;           *(u32x4*)(ymix + ((size_t)r0 + tok) * 1024 + 512 + c8) = w; } }
	v_add_f32_dpp v244, v244, v244 row_mirror row_mask:0xf bank_mask:0xf bound_ctrl:1
	v_add_f32_dpp v245, v245, v245 row_mirror row_mask:0xf bank_mask:0xf bound_ctrl:1
	v_add_f32_dpp v246, v246, v246 row_mirror row_mask:0xf bank_mask:0xf bound_ctrl:1
	v_add_f32_dpp v247, v247, v247 row_mirror row_mask:0xf bank_mask:0xf bound_ctrl:1
	v_add_f32_dpp v248, v248, v248 row_mirror row_mask:0xf bank_mask:0xf bound_ctrl:1
	v_add_f32_dpp v249, v249, v249 row_mirror row_mask:0xf bank_mask:0xf bound_ctrl:1
	v_add_f32_dpp v250, v250, v250 row_mirror row_mask:0xf bank_mask:0xf bound_ctrl:1
	v_add_f32_dpp v251, v251, v251 row_mirror row_mask:0xf bank_mask:0xf bound_ctrl:1
	v_add_f32_dpp v252, v252, v252 row_mirror row_mask:0xf bank_mask:0xf bound_ctrl:1
	v_mov_b32_e32 v176, v242
	v_mov_b32_e32 v177, v243
	v_mov_b32_e32 v178, v244
	v_mov_b32_e32 v179, v245
	v_mov_b32_e32 v180, v246
	v_mov_b32_e32 v181, v247
	v_mov_b32_e32 v182, v248
	v_mov_b32_e32 v183, v249
	v_mov_b32_e32 v204, v250
	v_mov_b32_e32 v205, v251
	v_mov_b32_e32 v206, v252
	v_permlane16_swap_b32 v242, v176
	v_permlane16_swap_b32 v243, v177
	v_permlane16_swap_b32 v244, v178
	v_permlane16_swap_b32 v245, v179
	v_permlane16_swap_b32 v246, v180
	v_permlane16_swap_b32 v247, v181
	v_permlane16_swap_b32 v248, v182
	v_permlane16_swap_b32 v249, v183
	v_permlane16_swap_b32 v250, v204
	v_permlane16_swap_b32 v251, v205
	v_permlane16_swap_b32 v252, v206
	v_add_f32_e32 v242, v242, v176
	v_add_f32_e32 v243, v243, v177
	v_add_f32_e32 v244, v244, v178
	v_add_f32_e32 v245, v245, v179
	v_add_f32_e32 v246, v246, v180
	v_add_f32_e32 v247, v247, v181
	v_add_f32_e32 v248, v248, v182
	v_add_f32_e32 v249, v249, v183
	v_add_f32_e32 v250, v250, v204
	v_add_f32_e32 v251, v251, v205
	v_add_f32_e32 v252, v252, v206
	v_mov_b32_e32 v176, v242
	v_mov_b32_e32 v177, v243
	v_mov_b32_e32 v178, v244
	v_mov_b32_e32 v179, v245
	v_mov_b32_e32 v180, v246
	v_mov_b32_e32 v181, v247
	v_mov_b32_e32 v182, v248
	v_mov_b32_e32 v183, v249
	v_mov_b32_e32 v204, v250
	v_mov_b32_e32 v205, v251
	v_mov_b32_e32 v206, v252
	v_permlane32_swap_b32 v242, v176
	v_permlane32_swap_b32 v243, v177
	v_permlane32_swap_b32 v244, v178
	v_permlane32_swap_b32 v245, v179
	v_permlane32_swap_b32 v246, v180
	v_permlane32_swap_b32 v247, v181
	v_permlane32_swap_b32 v248, v182
	v_permlane32_swap_b32 v249, v183
	v_permlane32_swap_b32 v250, v204
	v_permlane32_swap_b32 v251, v205
	v_permlane32_swap_b32 v252, v206
	v_add_f32_e32 v242, v242, v176
	v_add_f32_e32 v243, v243, v177
	v_add_f32_e32 v244, v244, v178
	v_add_f32_e32 v245, v245, v179
	v_add_f32_e32 v246, v246, v180
	v_add_f32_e32 v247, v247, v181
	v_add_f32_e32 v248, v248, v182
	v_add_f32_e32 v249, v249, v183
	v_add_f32_e32 v250, v250, v204
	v_add_f32_e32 v251, v251, v205
	v_add_f32_e32 v252, v252, v206
	s_waitcnt lgkmcnt(0)
	v_mul_f32_e32 v242, v213, v242
	v_mul_f32_e32 v243, v215, v243
	v_mul_f32_e32 v244, v217, v244
	v_mul_f32_e32 v245, v219, v245
	v_mul_f32_e32 v246, v221, v246
	v_mul_f32_e32 v247, v223, v247
	v_mul_f32_e32 v248, v225, v248
	v_mul_f32_e32 v249, v227, v249
	v_mul_f32_e32 v250, v229, v250
	v_mul_f32_e32 v251, v231, v251
	v_mul_f32_e32 v252, v233, v252
	v_mul_f32_e32 v212, v153, v212
	v_mul_f32_e32 v214, v153, v214
	v_mul_f32_e32 v216, v153, v216
	v_mul_f32_e32 v218, v153, v218
	v_mul_f32_e32 v220, v153, v220
	v_mul_f32_e32 v222, v153, v222
	v_mul_f32_e32 v224, v153, v224
	v_mul_f32_e32 v226, v153, v226
	v_mul_f32_e32 v228, v153, v228
	v_mul_f32_e32 v230, v153, v230
	v_mul_f32_e32 v232, v153, v232
	v_add_f32_e32 v212, v147, v212
	v_add_f32_e32 v214, v147, v214
	v_add_f32_e32 v216, v147, v216
	v_add_f32_e32 v218, v147, v218
	v_add_f32_e32 v220, v147, v220
	v_add_f32_e32 v222, v147, v222
	v_add_f32_e32 v224, v147, v224
	v_add_f32_e32 v226, v147, v226
	v_add_f32_e32 v228, v147, v228
	v_add_f32_e32 v230, v147, v230
	v_add_f32_e32 v232, v147, v232
	v_add_f32_e32 v242, v242, v212
	v_add_f32_e32 v243, v243, v214
	v_add_f32_e32 v244, v244, v216
	v_add_f32_e32 v245, v245, v218
	v_add_f32_e32 v246, v246, v220
	v_add_f32_e32 v247, v247, v222
	v_add_f32_e32 v248, v248, v224
	v_add_f32_e32 v249, v249, v226
	v_add_f32_e32 v250, v250, v228
	v_add_f32_e32 v251, v251, v230
	v_add_f32_e32 v252, v252, v232
	v_mul_f32_e32 v242, v128, v242
	v_mul_f32_e32 v243, v129, v243
	v_mul_f32_e32 v244, v130, v244
	v_mul_f32_e32 v245, v131, v245
	v_mul_f32_e32 v246, v132, v246
	v_mul_f32_e32 v247, v133, v247
	v_mul_f32_e32 v248, v134, v248
	v_mul_f32_e32 v249, v135, v249
	v_mul_f32_e32 v250, v136, v250
	v_mul_f32_e32 v251, v137, v251
	v_mul_f32_e32 v252, v138, v252
	ds_write_b32 v198, v242 offset:8704
	ds_write_b32 v198, v243 offset:10752
	ds_write_b32 v198, v244 offset:12800
	ds_write_b32 v198, v245 offset:14848
	ds_write_b32 v198, v246 offset:16896
	ds_write_b32 v198, v247 offset:18944
	ds_write_b32 v198, v248 offset:20992
	ds_write_b32 v198, v249 offset:23040
	ds_write_b32 v198, v250 offset:25088
	ds_write_b32 v198, v251 offset:27136
	ds_write_b32 v198, v252 offset:29184
	s_waitcnt lgkmcnt(0)
	s_barrier
	s_and_saveexec_b64 s[0:1], s[10:11]
	s_cbranch_execz .LBB0_497
	ds_read_b128 v[128:131], v194 offset:8704
	ds_read_b128 v[132:135], v194 offset:8720
	s_waitcnt lgkmcnt(1)
	v_cvt_pk_bf16_f32 v128, v128, v129
	v_cvt_pk_bf16_f32 v129, v130, v131
	s_waitcnt lgkmcnt(0)
	v_cvt_pk_bf16_f32 v130, v132, v133
	v_lshl_add_u64 v[132:133], v[168:169], 0, v[170:171]
	v_cvt_pk_bf16_f32 v131, v134, v135
	global_store_dwordx4 v[132:133], v[128:131], off offset:1024
